# MoBA loop head: wave-uniform any-lane-selected test reads the v_cmp mask directly (ballot trimmed, docs 7.12)
# baseline (speedup 1.0000x reference)
; template <int DQK, bool MOBA>
; __device__ __forceinline__ void attn_unit(const Args& A, int b, int h, int qb, lptr lds) {
;     ...
;         const int tt = t & 3; const bool diag = t < 4; const int blk = diag ? own : ((t - 4) >> 2);
;         const bool lsel = diag || ((sel >> blk) & 1u);
;         bool act;
;         if (diag) act = (64 * tt < 32 * (wid + 1));
;         else act = MOBA ? (__ballot(lsel) != 0ull) : true;
;         if (act) {
.LBB0_789:
	s_cmp_lt_u32 s6, 4
	s_cselect_b64 s[4:5], -1, 0
	s_add_i32 s0, s15, -6
	s_ashr_i32 s0, s0, 2
	v_lshrrev_b32_e32 v80, s0, v172
	v_and_b32_e32 v80, 1, v80
	s_cmp_gt_u32 s6, 3
	v_cmp_eq_u32_e64 s[0:1], 1, v80
	s_mov_b64 s[28:29], -1
	s_cbranch_scc0 .LBB0_792
	s_nop 3
	s_cmp_lg_u64 s[0:1], 0
	s_cbranch_scc0 .Lmoba_skip
	s_branch .LBB0_794
